# gla_scan sample rows: the 4 steps' v/a/q/k loads issued up front instead of a dependent wait chain per step
# speedup vs baseline: 1.0114x; 1.0018x over previous
; DI float bflo(unsigned w) { return __uint_as_float(w << 16); }
; DI float bfhi(unsigned w) { return __uint_as_float(w & 0xffff0000u); }
; DI float bf2f(bf16_t b) { return __uint_as_float(((unsigned)b) << 16); }
; DI void gla_scan(const Params& P, LAS unsigned char* lds) {
;     ...
;         const int b = it >> 2, h = it & 3; const int v4 = lane * 4;
;         const float* S0 = P.in[I_SGLA] + ((size_t)(b * 4 + h) * 128 + 16 * wid) * 256 + v4;
;         f32x4 S[16];
; #pragma unroll
;         for (int i = 0; i < 16; ++i) S[i] = *(const f32x4*)(S0 + (size_t)i * 256);
; #pragma unroll
;         for (int t = 0; t < 4; ++t) { const int row = TP + 4 * b + t; const bf16_t* qk = QK + (size_t)row * 3072;
;             const u32x2 vw = *(const u32x2*)(qk + 1024 + h * 256 + v4); const f32x4 v = {bflo(vw.x), bfhi(vw.x), bflo(vw.y), bfhi(vw.y)};
;             f32x4 po = {0.f, 0.f, 0.f, 0.f};
;             const int dl = h * 128 + 16 * wid + (lane & 15);
;             const float a_l = SA[(size_t)(4 * b + t) * 512 + dl]; const float q_l = bf2f(qk[dl]), k_l = bf2f(qk[512 + dl]);
; #pragma unroll
;             for (int i = 0; i < 16; ++i) { const float a = __builtin_bit_cast(float, __builtin_amdgcn_readlane(__builtin_bit_cast(int, a_l), i));
;                 const float q = __builtin_bit_cast(float, __builtin_amdgcn_readlane(__builtin_bit_cast(int, q_l), i)), k = __builtin_bit_cast(float, __builtin_amdgcn_readlane(__builtin_bit_cast(int, k_l), i));
;                 S[i] = S[i] * a + v * k; po += S[i] * q; }
.LBB0_1096:
	s_ashr_i32 s7, s6, 31
	s_lshl_b64 s[12:13], s[6:7], 15
	s_add_u32 s12, s12, s10
	s_addc_u32 s13, s13, s11
	s_lshl_b64 s[12:13], s[12:13], 2
	v_lshl_add_u64 v[0:1], v[52:53], 0, s[12:13]
	s_and_b32 s14, s6, -4
	v_add_co_u32_e32 v2, vcc, s86, v0
	s_mul_i32 s7, s14, 0x1800
	s_nop 0
	v_addc_co_u32_e32 v3, vcc, 0, v1, vcc
	s_and_b32 s15, s6, 3
	s_add_i32 s3, s14, 0x4000
	s_add_i32 s16, s7, 0x6000000
	v_add_co_u32_e32 v4, vcc, s92, v0
	s_mul_hi_i32 s17, s3, 0x1800
	s_add_u32 s16, s4, s16
	v_addc_co_u32_e32 v5, vcc, 0, v1, vcc
	s_addc_u32 s17, s5, s17
	s_lshl_b32 s36, s15, 9
	global_load_dwordx4 v[62:65], v[0:1], off
	global_load_dwordx4 v[66:69], v[0:1], off offset:1024
	global_load_dwordx4 v[70:73], v[0:1], off offset:2048
	global_load_dwordx4 v[74:77], v[0:1], off offset:3072
	v_add_co_u32_e32 v0, vcc, s91, v0
	s_add_u32 s18, s16, s36
	s_nop 0
	v_addc_co_u32_e32 v1, vcc, 0, v1, vcc
	s_addc_u32 s19, s17, 0
	global_load_dwordx4 v[46:49], v[4:5], off offset:-4096
	global_load_dwordx4 v[42:45], v[2:3], off offset:1024
	global_load_dwordx4 v[38:41], v[2:3], off offset:2048
	global_load_dwordx4 v[34:37], v[2:3], off offset:3072
	global_load_dwordx4 v[30:33], v[4:5], off
	global_load_dwordx4 v[26:29], v[4:5], off offset:1024
	global_load_dwordx4 v[20:23], v[4:5], off offset:2048
	global_load_dwordx4 v[16:19], v[4:5], off offset:3072
	global_load_dwordx4 v[12:15], v[0:1], off
	global_load_dwordx4 v[8:11], v[0:1], off offset:1024
	s_nop 0
	global_load_dwordx4 v[4:7], v[0:1], off offset:2048
	s_nop 0
	global_load_dwordx4 v[0:3], v[0:1], off offset:3072
	s_waitcnt vmcnt(17)
	v_lshl_add_u32 v58, s15, 7, v96
	global_load_dwordx2 v[60:61], v99, s[18:19] offset:2048
	v_ashrrev_i32_e32 v59, 31, v58
	s_ashr_i32 s15, s14, 31
	v_lshl_add_u64 v[56:57], v[58:59], 2, s[8:9]
	s_lshl_b64 s[18:19], s[14:15], 11
	v_lshlrev_b64 v[58:59], 1, v[58:59]
	s_add_i32 s15, s14, 0x4001
	s_mul_hi_i32 s15, s15, 0x1800
	s_mov_b32 s18, s14
	s_ashr_i32 s19, s18, 31
	s_lshl_b64 s[18:19], s[18:19], 11
	v_lshl_add_u64 v[240:241], v[56:57], 0, s[18:19]
	global_load_dword v218, v[240:241], off
	s_add_i32 s18, s3, 0
	s_mul_hi_i32 s19, s18, 0x1800
	s_mul_i32 s18, s18, 0x1800
	s_add_u32 s18, s4, s18
	s_addc_u32 s19, s5, s19
	v_lshl_add_u64 v[242:243], s[18:19], 0, v[58:59]
	global_load_ushort v219, v[242:243], off
	global_load_ushort v220, v[242:243], off offset:1024
	s_or_b32 s18, s14, 1
	s_ashr_i32 s19, s18, 31
	s_lshl_b64 s[18:19], s[18:19], 11
	v_lshl_add_u64 v[240:241], v[56:57], 0, s[18:19]
	global_load_dword v224, v[240:241], off
	s_add_i32 s18, s3, 1
	s_mul_hi_i32 s19, s18, 0x1800
	s_mul_i32 s18, s18, 0x1800
	s_add_u32 s18, s4, s18
	s_addc_u32 s19, s5, s19
	v_lshl_add_u64 v[242:243], s[18:19], 0, v[58:59]
	global_load_ushort v225, v[242:243], off
	global_load_ushort v226, v[242:243], off offset:1024
	s_add_u32 s18, s18, s36
	s_addc_u32 s19, s19, 0
	global_load_dwordx2 v[222:223], v99, s[18:19] offset:2048
	s_or_b32 s18, s14, 2
	s_ashr_i32 s19, s18, 31
	s_lshl_b64 s[18:19], s[18:19], 11
	v_lshl_add_u64 v[240:241], v[56:57], 0, s[18:19]
	global_load_dword v230, v[240:241], off
	s_add_i32 s18, s3, 2
	s_mul_hi_i32 s19, s18, 0x1800
	s_mul_i32 s18, s18, 0x1800
	s_add_u32 s18, s4, s18
	s_addc_u32 s19, s5, s19
	v_lshl_add_u64 v[242:243], s[18:19], 0, v[58:59]
	global_load_ushort v231, v[242:243], off
	global_load_ushort v232, v[242:243], off offset:1024
	s_add_u32 s18, s18, s36
	s_addc_u32 s19, s19, 0
	global_load_dwordx2 v[228:229], v99, s[18:19] offset:2048
	s_or_b32 s18, s14, 3
	s_ashr_i32 s19, s18, 31
	s_lshl_b64 s[18:19], s[18:19], 11
	v_lshl_add_u64 v[240:241], v[56:57], 0, s[18:19]
	global_load_dword v236, v[240:241], off
	s_add_i32 s18, s3, 3
	s_mul_hi_i32 s19, s18, 0x1800
	s_mul_i32 s18, s18, 0x1800
	s_add_u32 s18, s4, s18
	s_addc_u32 s19, s5, s19
	v_lshl_add_u64 v[242:243], s[18:19], 0, v[58:59]
	global_load_ushort v237, v[242:243], off
	global_load_ushort v238, v[242:243], off offset:1024
	s_add_u32 s18, s18, s36
	s_addc_u32 s19, s19, 0
	global_load_dwordx2 v[234:235], v99, s[18:19] offset:2048
	s_waitcnt vmcnt(0)
	v_lshlrev_b32_e32 v78, 16, v60
	v_and_b32_e32 v79, 0xffff0000, v60
	v_lshlrev_b32_e32 v80, 16, v61
	v_and_b32_e32 v81, 0xffff0000, v61
	v_mov_b32_e32 v88, v218
	v_lshlrev_b32_e32 v89, 16, v219
	v_lshlrev_b32_e32 v90, 16, v220
	s_nop 0
	v_readlane_b32 s16, v88, 0
	v_readlane_b32 s20, v90, 0
	v_readlane_b32 s18, v89, 0
	s_nop 0
	v_pk_mul_f32 v[82:83], s[20:21], v[78:79] op_sel_hi:[0,1]
	v_pk_mul_f32 v[60:61], s[20:21], v[80:81] op_sel_hi:[0,1]
	v_readlane_b32 s20, v90, 1
	v_pk_fma_f32 v[60:61], v[64:65], s[16:17], v[60:61] op_sel_hi:[1,0,1]
	v_pk_fma_f32 v[62:63], v[62:63], s[16:17], v[82:83] op_sel_hi:[1,0,1]
	v_readlane_b32 s16, v88, 1
	v_pk_mul_f32 v[86:87], s[20:21], v[80:81] op_sel_hi:[0,1]
	v_pk_mul_f32 v[64:65], s[20:21], v[78:79] op_sel_hi:[0,1]
	v_readlane_b32 s20, v90, 2
	v_pk_fma_f32 v[82:83], s[18:19], v[62:63], 0 op_sel_hi:[0,1,0]
	v_pk_fma_f32 v[84:85], s[18:19], v[60:61], 0 op_sel_hi:[0,1,0]
	v_readlane_b32 s18, v89, 1
	v_pk_fma_f32 v[64:65], v[66:67], s[16:17], v[64:65] op_sel_hi:[1,0,1]
	v_pk_fma_f32 v[66:67], v[68:69], s[16:17], v[86:87] op_sel_hi:[1,0,1]
	v_readlane_b32 s16, v88, 2
	v_pk_mul_f32 v[86:87], s[20:21], v[78:79] op_sel_hi:[0,1]
	v_pk_mul_f32 v[68:69], s[20:21], v[80:81] op_sel_hi:[0,1]
	v_readlane_b32 s20, v90, 3
	v_pk_fma_f32 v[84:85], s[18:19], v[66:67], v[84:85] op_sel_hi:[0,1,1]
	v_pk_fma_f32 v[82:83], s[18:19], v[64:65], v[82:83] op_sel_hi:[0,1,1]
	v_readlane_b32 s18, v89, 2
	v_pk_fma_f32 v[68:69], v[72:73], s[16:17], v[68:69] op_sel_hi:[1,0,1]
	v_pk_fma_f32 v[70:71], v[70:71], s[16:17], v[86:87] op_sel_hi:[1,0,1]
; DI void gla_scan(const Params& P, LAS unsigned char* lds) {
;     ...
; #pragma unroll
;             for (int i = 0; i < 16; ++i) { const float a = __builtin_bit_cast(float, __builtin_amdgcn_readlane(__builtin_bit_cast(int, a_l), i));
;                 const float q = __builtin_bit_cast(float, __builtin_amdgcn_readlane(__builtin_bit_cast(int, q_l), i)), k = __builtin_bit_cast(float, __builtin_amdgcn_readlane(__builtin_bit_cast(int, k_l), i));
;                 S[i] = S[i] * a + v * k; po += S[i] * q; }
	v_readlane_b32 s16, v88, 3
	v_pk_mul_f32 v[86:87], s[20:21], v[80:81] op_sel_hi:[0,1]
	v_pk_mul_f32 v[72:73], s[20:21], v[78:79] op_sel_hi:[0,1]
	v_pk_fma_f32 v[82:83], s[18:19], v[70:71], v[82:83] op_sel_hi:[0,1,1]
	v_pk_fma_f32 v[84:85], s[18:19], v[68:69], v[84:85] op_sel_hi:[0,1,1]
	v_readlane_b32 s18, v89, 3
	v_pk_fma_f32 v[72:73], v[74:75], s[16:17], v[72:73] op_sel_hi:[1,0,1]
	v_pk_fma_f32 v[74:75], v[76:77], s[16:17], v[86:87] op_sel_hi:[1,0,1]
	v_readlane_b32 s20, v90, 4
	v_pk_fma_f32 v[76:77], s[18:19], v[74:75], v[84:85] op_sel_hi:[0,1,1]
	v_readlane_b32 s16, v88, 4
	v_pk_mul_f32 v[84:85], s[20:21], v[78:79] op_sel_hi:[0,1]
	v_pk_mul_f32 v[86:87], s[20:21], v[80:81] op_sel_hi:[0,1]
	v_readlane_b32 s20, v90, 5
	v_pk_fma_f32 v[48:49], v[48:49], s[16:17], v[86:87] op_sel_hi:[1,0,1]
	v_pk_fma_f32 v[46:47], v[46:47], s[16:17], v[84:85] op_sel_hi:[1,0,1]
	v_readlane_b32 s16, v88, 5
	v_pk_mul_f32 v[84:85], s[20:21], v[80:81] op_sel_hi:[0,1]
	v_pk_mul_f32 v[86:87], s[20:21], v[78:79] op_sel_hi:[0,1]
	v_readlane_b32 s20, v90, 6
	v_pk_fma_f32 v[42:43], v[42:43], s[16:17], v[86:87] op_sel_hi:[1,0,1]
	v_pk_fma_f32 v[44:45], v[44:45], s[16:17], v[84:85] op_sel_hi:[1,0,1]
	v_readlane_b32 s16, v88, 6
	v_pk_mul_f32 v[84:85], s[20:21], v[78:79] op_sel_hi:[0,1]
	v_pk_mul_f32 v[86:87], s[20:21], v[80:81] op_sel_hi:[0,1]
	v_readlane_b32 s20, v90, 7
	v_pk_fma_f32 v[82:83], s[18:19], v[72:73], v[82:83] op_sel_hi:[0,1,1]
	v_readlane_b32 s18, v89, 4
	v_pk_fma_f32 v[40:41], v[40:41], s[16:17], v[86:87] op_sel_hi:[1,0,1]
	v_pk_fma_f32 v[38:39], v[38:39], s[16:17], v[84:85] op_sel_hi:[1,0,1]
	v_readlane_b32 s16, v88, 7
	v_pk_mul_f32 v[84:85], s[20:21], v[80:81] op_sel_hi:[0,1]
	v_pk_mul_f32 v[86:87], s[20:21], v[78:79] op_sel_hi:[0,1]
	v_readlane_b32 s20, v90, 8
	v_pk_fma_f32 v[82:83], s[18:19], v[46:47], v[82:83] op_sel_hi:[0,1,1]
	v_pk_fma_f32 v[76:77], s[18:19], v[48:49], v[76:77] op_sel_hi:[0,1,1]
	v_readlane_b32 s18, v89, 5
	v_pk_fma_f32 v[34:35], v[34:35], s[16:17], v[86:87] op_sel_hi:[1,0,1]
	v_pk_fma_f32 v[36:37], v[36:37], s[16:17], v[84:85] op_sel_hi:[1,0,1]
	v_readlane_b32 s16, v88, 8
	v_pk_mul_f32 v[84:85], s[20:21], v[78:79] op_sel_hi:[0,1]
	v_pk_mul_f32 v[86:87], s[20:21], v[80:81] op_sel_hi:[0,1]
	v_readlane_b32 s20, v90, 9
	v_pk_fma_f32 v[76:77], s[18:19], v[44:45], v[76:77] op_sel_hi:[0,1,1]
	v_pk_fma_f32 v[82:83], s[18:19], v[42:43], v[82:83] op_sel_hi:[0,1,1]
	v_readlane_b32 s18, v89, 6
	v_pk_fma_f32 v[32:33], v[32:33], s[16:17], v[86:87] op_sel_hi:[1,0,1]
	v_pk_fma_f32 v[30:31], v[30:31], s[16:17], v[84:85] op_sel_hi:[1,0,1]
	v_readlane_b32 s16, v88, 9
	v_pk_mul_f32 v[84:85], s[20:21], v[80:81] op_sel_hi:[0,1]
	v_pk_mul_f32 v[86:87], s[20:21], v[78:79] op_sel_hi:[0,1]
	v_readlane_b32 s20, v90, 10
	v_pk_fma_f32 v[82:83], s[18:19], v[38:39], v[82:83] op_sel_hi:[0,1,1]
	v_pk_fma_f32 v[76:77], s[18:19], v[40:41], v[76:77] op_sel_hi:[0,1,1]
	v_readlane_b32 s18, v89, 7
	v_pk_fma_f32 v[26:27], v[26:27], s[16:17], v[86:87] op_sel_hi:[1,0,1]
	v_pk_fma_f32 v[28:29], v[28:29], s[16:17], v[84:85] op_sel_hi:[1,0,1]
	v_readlane_b32 s16, v88, 10
	v_pk_mul_f32 v[84:85], s[20:21], v[78:79] op_sel_hi:[0,1]
	v_pk_mul_f32 v[86:87], s[20:21], v[80:81] op_sel_hi:[0,1]
	v_readlane_b32 s20, v90, 11
	v_pk_fma_f32 v[76:77], s[18:19], v[36:37], v[76:77] op_sel_hi:[0,1,1]
	v_pk_fma_f32 v[82:83], s[18:19], v[34:35], v[82:83] op_sel_hi:[0,1,1]
	v_readlane_b32 s18, v89, 8
	v_pk_fma_f32 v[22:23], v[22:23], s[16:17], v[86:87] op_sel_hi:[1,0,1]
	v_pk_fma_f32 v[20:21], v[20:21], s[16:17], v[84:85] op_sel_hi:[1,0,1]
	v_readlane_b32 s16, v88, 11
	v_pk_mul_f32 v[84:85], s[20:21], v[80:81] op_sel_hi:[0,1]
	v_pk_mul_f32 v[86:87], s[20:21], v[78:79] op_sel_hi:[0,1]
	v_readlane_b32 s20, v90, 12
	v_pk_fma_f32 v[82:83], s[18:19], v[30:31], v[82:83] op_sel_hi:[0,1,1]
	v_pk_fma_f32 v[76:77], s[18:19], v[32:33], v[76:77] op_sel_hi:[0,1,1]
	v_readlane_b32 s18, v89, 9
	v_pk_fma_f32 v[16:17], v[16:17], s[16:17], v[86:87] op_sel_hi:[1,0,1]
	v_pk_fma_f32 v[18:19], v[18:19], s[16:17], v[84:85] op_sel_hi:[1,0,1]
	v_readlane_b32 s16, v88, 12
	v_pk_mul_f32 v[84:85], s[20:21], v[78:79] op_sel_hi:[0,1]
	v_pk_mul_f32 v[86:87], s[20:21], v[80:81] op_sel_hi:[0,1]
	v_readlane_b32 s20, v90, 13
	v_pk_fma_f32 v[76:77], s[18:19], v[28:29], v[76:77] op_sel_hi:[0,1,1]
	v_pk_fma_f32 v[82:83], s[18:19], v[26:27], v[82:83] op_sel_hi:[0,1,1]
	v_readlane_b32 s18, v89, 10
	v_pk_fma_f32 v[14:15], v[14:15], s[16:17], v[86:87] op_sel_hi:[1,0,1]
	v_pk_fma_f32 v[12:13], v[12:13], s[16:17], v[84:85] op_sel_hi:[1,0,1]
	v_readlane_b32 s16, v88, 13
	v_pk_mul_f32 v[84:85], s[20:21], v[80:81] op_sel_hi:[0,1]
	v_pk_mul_f32 v[86:87], s[20:21], v[78:79] op_sel_hi:[0,1]
	v_readlane_b32 s20, v90, 14
	v_pk_fma_f32 v[82:83], s[18:19], v[20:21], v[82:83] op_sel_hi:[0,1,1]
	v_pk_fma_f32 v[76:77], s[18:19], v[22:23], v[76:77] op_sel_hi:[0,1,1]
	v_readlane_b32 s18, v89, 11
	v_pk_fma_f32 v[8:9], v[8:9], s[16:17], v[86:87] op_sel_hi:[1,0,1]
	v_pk_fma_f32 v[10:11], v[10:11], s[16:17], v[84:85] op_sel_hi:[1,0,1]
	v_readlane_b32 s16, v88, 14
	v_pk_mul_f32 v[84:85], s[20:21], v[78:79] op_sel_hi:[0,1]
	v_pk_mul_f32 v[86:87], s[20:21], v[80:81] op_sel_hi:[0,1]
	v_readlane_b32 s20, v90, 15
	v_pk_fma_f32 v[76:77], s[18:19], v[18:19], v[76:77] op_sel_hi:[0,1,1]
	v_pk_fma_f32 v[82:83], s[18:19], v[16:17], v[82:83] op_sel_hi:[0,1,1]
	v_readlane_b32 s18, v89, 12
	v_pk_fma_f32 v[6:7], v[6:7], s[16:17], v[86:87] op_sel_hi:[1,0,1]
	v_pk_fma_f32 v[4:5], v[4:5], s[16:17], v[84:85] op_sel_hi:[1,0,1]
	v_readlane_b32 s16, v88, 15
	v_pk_mul_f32 v[80:81], s[20:21], v[80:81] op_sel_hi:[0,1]
	v_pk_mul_f32 v[78:79], s[20:21], v[78:79] op_sel_hi:[0,1]
; #define LAS __attribute__((address_space(3)))
; DI float bflo(unsigned w) { return __uint_as_float(w << 16); }
; DI float bfhi(unsigned w) { return __uint_as_float(w & 0xffff0000u); }
; DI float bf2f(bf16_t b) { return __uint_as_float(((unsigned)b) << 16); }
; DI void gla_scan(const Params& P, LAS unsigned char* lds) {
;     ...
;         for (int t = 0; t < 4; ++t) { const int row = TP + 4 * b + t; const bf16_t* qk = QK + (size_t)row * 3072;
;             const u32x2 vw = *(const u32x2*)(qk + 1024 + h * 256 + v4); const f32x4 v = {bflo(vw.x), bfhi(vw.x), bflo(vw.y), bfhi(vw.y)};
;             f32x4 po = {0.f, 0.f, 0.f, 0.f};
;             const int dl = h * 128 + 16 * wid + (lane & 15);
;             const float a_l = SA[(size_t)(4 * b + t) * 512 + dl]; const float q_l = bf2f(qk[dl]), k_l = bf2f(qk[512 + dl]);
; #pragma unroll
;             for (int i = 0; i < 16; ++i) { const float a = __builtin_bit_cast(float, __builtin_amdgcn_readlane(__builtin_bit_cast(int, a_l), i));
;                 const float q = __builtin_bit_cast(float, __builtin_amdgcn_readlane(__builtin_bit_cast(int, q_l), i)), k = __builtin_bit_cast(float, __builtin_amdgcn_readlane(__builtin_bit_cast(int, k_l), i));
;                 S[i] = S[i] * a + v * k; po += S[i] * q; }
;             *(LAS f32x4*)(red + (t * 8 + wid) * 256 + v4) = po; }
	v_pk_fma_f32 v[82:83], s[18:19], v[12:13], v[82:83] op_sel_hi:[0,1,1]
	v_pk_fma_f32 v[76:77], s[18:19], v[14:15], v[76:77] op_sel_hi:[0,1,1]
	v_readlane_b32 s18, v89, 13
	v_pk_fma_f32 v[0:1], v[0:1], s[16:17], v[78:79] op_sel_hi:[1,0,1]
	v_pk_fma_f32 v[2:3], v[2:3], s[16:17], v[80:81] op_sel_hi:[1,0,1]
	s_add_i32 s16, s7, 0x6001800
	v_pk_fma_f32 v[76:77], s[18:19], v[10:11], v[76:77] op_sel_hi:[0,1,1]
	v_pk_fma_f32 v[82:83], s[18:19], v[8:9], v[82:83] op_sel_hi:[0,1,1]
	v_readlane_b32 s18, v89, 14
	s_add_u32 s16, s4, s16
	s_addc_u32 s17, s5, s15
	v_pk_fma_f32 v[82:83], s[18:19], v[4:5], v[82:83] op_sel_hi:[0,1,1]
	v_pk_fma_f32 v[76:77], s[18:19], v[6:7], v[76:77] op_sel_hi:[0,1,1]
	v_readlane_b32 s18, v89, 15
	s_nop 1
	v_pk_fma_f32 v[78:79], s[18:19], v[2:3], v[76:77] op_sel_hi:[0,1,1]
	v_pk_fma_f32 v[76:77], s[18:19], v[0:1], v[82:83] op_sel_hi:[0,1,1]
	s_add_u32 s18, s16, s36
	s_addc_u32 s19, s17, 0
	ds_write_b128 v97, v[76:79]
	s_add_i32 s15, s14, 0x4002
	s_mul_hi_i32 s15, s15, 0x1800
	v_lshlrev_b32_e32 v102, 16, v222
	v_and_b32_e32 v103, 0xffff0000, v222
	v_lshlrev_b32_e32 v104, 16, v223
	v_and_b32_e32 v105, 0xffff0000, v223
	v_mov_b32_e32 v106, v224
	v_lshlrev_b32_e32 v107, 16, v225
	v_lshlrev_b32_e32 v108, 16, v226
	s_nop 0
	v_readlane_b32 s16, v106, 0
	v_readlane_b32 s20, v108, 0
	v_readlane_b32 s18, v107, 0
	s_nop 0
	v_pk_mul_f32 v[76:77], s[20:21], v[102:103] op_sel_hi:[0,1]
	v_pk_mul_f32 v[78:79], s[20:21], v[104:105] op_sel_hi:[0,1]
	v_readlane_b32 s20, v108, 1
	v_pk_fma_f32 v[60:61], v[60:61], s[16:17], v[78:79] op_sel_hi:[1,0,1]
	v_pk_fma_f32 v[62:63], v[62:63], s[16:17], v[76:77] op_sel_hi:[1,0,1]
	v_readlane_b32 s16, v106, 1
	v_pk_mul_f32 v[80:81], s[20:21], v[104:105] op_sel_hi:[0,1]
	v_pk_mul_f32 v[82:83], s[20:21], v[102:103] op_sel_hi:[0,1]
	v_pk_fma_f32 v[76:77], s[18:19], v[62:63], 0 op_sel_hi:[0,1,0]
	v_pk_fma_f32 v[78:79], s[18:19], v[60:61], 0 op_sel_hi:[0,1,0]
	v_readlane_b32 s18, v107, 1
	v_pk_fma_f32 v[64:65], v[64:65], s[16:17], v[82:83] op_sel_hi:[1,0,1]
	v_pk_fma_f32 v[66:67], v[66:67], s[16:17], v[80:81] op_sel_hi:[1,0,1]
	v_readlane_b32 s20, v108, 2
	v_pk_fma_f32 v[80:81], s[18:19], v[66:67], v[78:79] op_sel_hi:[0,1,1]
	v_pk_fma_f32 v[82:83], s[18:19], v[64:65], v[76:77] op_sel_hi:[0,1,1]
	v_readlane_b32 s16, v106, 2
	v_pk_mul_f32 v[78:79], s[20:21], v[102:103] op_sel_hi:[0,1]
	v_pk_mul_f32 v[76:77], s[20:21], v[104:105] op_sel_hi:[0,1]
	v_readlane_b32 s18, v107, 2
	v_pk_fma_f32 v[76:77], v[68:69], s[16:17], v[76:77] op_sel_hi:[1,0,1]
	v_pk_fma_f32 v[78:79], v[70:71], s[16:17], v[78:79] op_sel_hi:[1,0,1]
	v_readlane_b32 s20, v108, 3
	v_pk_fma_f32 v[68:69], s[18:19], v[78:79], v[82:83] op_sel_hi:[0,1,1]
	v_pk_fma_f32 v[70:71], s[18:19], v[76:77], v[80:81] op_sel_hi:[0,1,1]
	v_readlane_b32 s16, v106, 3
	v_pk_mul_f32 v[82:83], s[20:21], v[104:105] op_sel_hi:[0,1]
	v_pk_mul_f32 v[80:81], s[20:21], v[102:103] op_sel_hi:[0,1]
	v_readlane_b32 s20, v108, 4
	v_readlane_b32 s18, v107, 3
	v_pk_fma_f32 v[80:81], v[72:73], s[16:17], v[80:81] op_sel_hi:[1,0,1]
	v_pk_fma_f32 v[82:83], v[74:75], s[16:17], v[82:83] op_sel_hi:[1,0,1]
	v_readlane_b32 s16, v106, 4
	v_pk_mul_f32 v[72:73], s[20:21], v[102:103] op_sel_hi:[0,1]
	v_pk_mul_f32 v[74:75], s[20:21], v[104:105] op_sel_hi:[0,1]
	v_pk_fma_f32 v[70:71], s[18:19], v[82:83], v[70:71] op_sel_hi:[0,1,1]
	v_pk_fma_f32 v[68:69], s[18:19], v[80:81], v[68:69] op_sel_hi:[0,1,1]
	v_readlane_b32 s18, v107, 4
	v_pk_fma_f32 v[48:49], v[48:49], s[16:17], v[74:75] op_sel_hi:[1,0,1]
	v_pk_fma_f32 v[84:85], v[46:47], s[16:17], v[72:73] op_sel_hi:[1,0,1]
	v_readlane_b32 s20, v108, 5
	v_pk_fma_f32 v[46:47], s[18:19], v[84:85], v[68:69] op_sel_hi:[0,1,1]
	v_pk_fma_f32 v[68:69], s[18:19], v[48:49], v[70:71] op_sel_hi:[0,1,1]
	v_readlane_b32 s16, v106, 5
	v_pk_mul_f32 v[70:71], s[20:21], v[104:105] op_sel_hi:[0,1]
	v_pk_mul_f32 v[72:73], s[20:21], v[102:103] op_sel_hi:[0,1]
	v_readlane_b32 s20, v108, 6
	v_readlane_b32 s18, v107, 5
	v_pk_fma_f32 v[42:43], v[42:43], s[16:17], v[72:73] op_sel_hi:[1,0,1]
	v_pk_fma_f32 v[44:45], v[44:45], s[16:17], v[70:71] op_sel_hi:[1,0,1]
	v_readlane_b32 s16, v106, 6
	v_pk_mul_f32 v[70:71], s[20:21], v[102:103] op_sel_hi:[0,1]
	v_pk_mul_f32 v[72:73], s[20:21], v[104:105] op_sel_hi:[0,1]
	v_pk_fma_f32 v[68:69], s[18:19], v[44:45], v[68:69] op_sel_hi:[0,1,1]
	v_pk_fma_f32 v[46:47], s[18:19], v[42:43], v[46:47] op_sel_hi:[0,1,1]
	v_readlane_b32 s18, v107, 6
	v_pk_fma_f32 v[40:41], v[40:41], s[16:17], v[72:73] op_sel_hi:[1,0,1]
	v_pk_fma_f32 v[86:87], v[38:39], s[16:17], v[70:71] op_sel_hi:[1,0,1]
	v_readlane_b32 s20, v108, 7
	v_pk_fma_f32 v[38:39], s[18:19], v[86:87], v[46:47] op_sel_hi:[0,1,1]
	v_pk_fma_f32 v[46:47], s[18:19], v[40:41], v[68:69] op_sel_hi:[0,1,1]
	v_readlane_b32 s16, v106, 7
	v_pk_mul_f32 v[68:69], s[20:21], v[104:105] op_sel_hi:[0,1]
	v_pk_mul_f32 v[70:71], s[20:21], v[102:103] op_sel_hi:[0,1]
	v_readlane_b32 s20, v108, 8
	v_readlane_b32 s18, v107, 7
	v_pk_fma_f32 v[34:35], v[34:35], s[16:17], v[70:71] op_sel_hi:[1,0,1]
	v_pk_fma_f32 v[36:37], v[36:37], s[16:17], v[68:69] op_sel_hi:[1,0,1]
	v_readlane_b32 s16, v106, 8
	v_pk_mul_f32 v[68:69], s[20:21], v[102:103] op_sel_hi:[0,1]
	v_pk_mul_f32 v[70:71], s[20:21], v[104:105] op_sel_hi:[0,1]
	v_pk_fma_f32 v[46:47], s[18:19], v[36:37], v[46:47] op_sel_hi:[0,1,1]
	v_pk_fma_f32 v[38:39], s[18:19], v[34:35], v[38:39] op_sel_hi:[0,1,1]
	v_readlane_b32 s18, v107, 8
	v_pk_fma_f32 v[32:33], v[32:33], s[16:17], v[70:71] op_sel_hi:[1,0,1]
	v_pk_fma_f32 v[88:89], v[30:31], s[16:17], v[68:69] op_sel_hi:[1,0,1]
	v_readlane_b32 s20, v108, 9
	v_pk_fma_f32 v[30:31], s[18:19], v[88:89], v[38:39] op_sel_hi:[0,1,1]
; #define LAS __attribute__((address_space(3)))
; DI float bflo(unsigned w) { return __uint_as_float(w << 16); }
; DI float bfhi(unsigned w) { return __uint_as_float(w & 0xffff0000u); }
; DI float bf2f(bf16_t b) { return __uint_as_float(((unsigned)b) << 16); }
; DI void gla_scan(const Params& P, LAS unsigned char* lds) {
;     ...
;         for (int t = 0; t < 4; ++t) { const int row = TP + 4 * b + t; const bf16_t* qk = QK + (size_t)row * 3072;
;             const u32x2 vw = *(const u32x2*)(qk + 1024 + h * 256 + v4); const f32x4 v = {bflo(vw.x), bfhi(vw.x), bflo(vw.y), bfhi(vw.y)};
;             f32x4 po = {0.f, 0.f, 0.f, 0.f};
;             const int dl = h * 128 + 16 * wid + (lane & 15);
;             const float a_l = SA[(size_t)(4 * b + t) * 512 + dl]; const float q_l = bf2f(qk[dl]), k_l = bf2f(qk[512 + dl]);
; #pragma unroll
;             for (int i = 0; i < 16; ++i) { const float a = __builtin_bit_cast(float, __builtin_amdgcn_readlane(__builtin_bit_cast(int, a_l), i));
;                 const float q = __builtin_bit_cast(float, __builtin_amdgcn_readlane(__builtin_bit_cast(int, q_l), i)), k = __builtin_bit_cast(float, __builtin_amdgcn_readlane(__builtin_bit_cast(int, k_l), i));
;                 S[i] = S[i] * a + v * k; po += S[i] * q; }
;             *(LAS f32x4*)(red + (t * 8 + wid) * 256 + v4) = po; }
	v_pk_fma_f32 v[38:39], s[18:19], v[32:33], v[46:47] op_sel_hi:[0,1,1]
	v_readlane_b32 s16, v106, 9
	v_pk_mul_f32 v[46:47], s[20:21], v[104:105] op_sel_hi:[0,1]
	v_pk_mul_f32 v[68:69], s[20:21], v[102:103] op_sel_hi:[0,1]
	v_readlane_b32 s20, v108, 10
	v_readlane_b32 s18, v107, 9
	v_pk_fma_f32 v[26:27], v[26:27], s[16:17], v[68:69] op_sel_hi:[1,0,1]
	v_pk_fma_f32 v[28:29], v[28:29], s[16:17], v[46:47] op_sel_hi:[1,0,1]
	v_readlane_b32 s16, v106, 10
	v_pk_mul_f32 v[46:47], s[20:21], v[102:103] op_sel_hi:[0,1]
	v_pk_mul_f32 v[68:69], s[20:21], v[104:105] op_sel_hi:[0,1]
	v_pk_fma_f32 v[38:39], s[18:19], v[28:29], v[38:39] op_sel_hi:[0,1,1]
	v_pk_fma_f32 v[30:31], s[18:19], v[26:27], v[30:31] op_sel_hi:[0,1,1]
	v_readlane_b32 s18, v107, 10
	v_pk_fma_f32 v[22:23], v[22:23], s[16:17], v[68:69] op_sel_hi:[1,0,1]
	v_pk_fma_f32 v[90:91], v[20:21], s[16:17], v[46:47] op_sel_hi:[1,0,1]
	v_readlane_b32 s20, v108, 11
	v_pk_fma_f32 v[20:21], s[18:19], v[90:91], v[30:31] op_sel_hi:[0,1,1]
	v_pk_fma_f32 v[30:31], s[18:19], v[22:23], v[38:39] op_sel_hi:[0,1,1]
	v_readlane_b32 s16, v106, 11
	v_pk_mul_f32 v[38:39], s[20:21], v[104:105] op_sel_hi:[0,1]
	v_pk_mul_f32 v[46:47], s[20:21], v[102:103] op_sel_hi:[0,1]
	v_readlane_b32 s20, v108, 12
	v_readlane_b32 s18, v107, 11
	v_pk_fma_f32 v[16:17], v[16:17], s[16:17], v[46:47] op_sel_hi:[1,0,1]
	v_pk_fma_f32 v[18:19], v[18:19], s[16:17], v[38:39] op_sel_hi:[1,0,1]
	v_readlane_b32 s16, v106, 12
	v_pk_mul_f32 v[38:39], s[20:21], v[102:103] op_sel_hi:[0,1]
	v_pk_mul_f32 v[46:47], s[20:21], v[104:105] op_sel_hi:[0,1]
	v_pk_fma_f32 v[30:31], s[18:19], v[18:19], v[30:31] op_sel_hi:[0,1,1]
	v_pk_fma_f32 v[20:21], s[18:19], v[16:17], v[20:21] op_sel_hi:[0,1,1]
	v_readlane_b32 s18, v107, 12
	v_pk_fma_f32 v[14:15], v[14:15], s[16:17], v[46:47] op_sel_hi:[1,0,1]
	v_pk_fma_f32 v[92:93], v[12:13], s[16:17], v[38:39] op_sel_hi:[1,0,1]
	v_readlane_b32 s20, v108, 13
	v_pk_fma_f32 v[12:13], s[18:19], v[92:93], v[20:21] op_sel_hi:[0,1,1]
	v_pk_fma_f32 v[20:21], s[18:19], v[14:15], v[30:31] op_sel_hi:[0,1,1]
	v_readlane_b32 s16, v106, 13
	v_pk_mul_f32 v[30:31], s[20:21], v[104:105] op_sel_hi:[0,1]
	v_pk_mul_f32 v[38:39], s[20:21], v[102:103] op_sel_hi:[0,1]
	v_readlane_b32 s20, v108, 14
	v_readlane_b32 s18, v107, 13
	v_pk_fma_f32 v[8:9], v[8:9], s[16:17], v[38:39] op_sel_hi:[1,0,1]
	v_pk_fma_f32 v[10:11], v[10:11], s[16:17], v[30:31] op_sel_hi:[1,0,1]
	v_readlane_b32 s16, v106, 14
	v_pk_mul_f32 v[30:31], s[20:21], v[102:103] op_sel_hi:[0,1]
	v_pk_mul_f32 v[38:39], s[20:21], v[104:105] op_sel_hi:[0,1]
	v_pk_fma_f32 v[20:21], s[18:19], v[10:11], v[20:21] op_sel_hi:[0,1,1]
	v_pk_fma_f32 v[12:13], s[18:19], v[8:9], v[12:13] op_sel_hi:[0,1,1]
	v_readlane_b32 s18, v107, 14
	v_pk_fma_f32 v[6:7], v[6:7], s[16:17], v[38:39] op_sel_hi:[1,0,1]
	v_pk_fma_f32 v[94:95], v[4:5], s[16:17], v[30:31] op_sel_hi:[1,0,1]
	v_readlane_b32 s20, v108, 15
	v_pk_fma_f32 v[4:5], s[18:19], v[94:95], v[12:13] op_sel_hi:[0,1,1]
	v_pk_fma_f32 v[12:13], s[18:19], v[6:7], v[20:21] op_sel_hi:[0,1,1]
	v_readlane_b32 s16, v106, 15
	v_pk_mul_f32 v[20:21], s[20:21], v[104:105] op_sel_hi:[0,1]
	v_pk_mul_f32 v[30:31], s[20:21], v[102:103] op_sel_hi:[0,1]
	v_pk_fma_f32 v[0:1], v[0:1], s[16:17], v[30:31] op_sel_hi:[1,0,1]
	v_pk_fma_f32 v[2:3], v[2:3], s[16:17], v[20:21] op_sel_hi:[1,0,1]
	s_add_i32 s16, s7, 0x6003000
	s_add_u32 s16, s4, s16
	v_readlane_b32 s18, v107, 15
	s_addc_u32 s17, s5, s15
	s_nop 0
	v_pk_fma_f32 v[70:71], s[18:19], v[2:3], v[12:13] op_sel_hi:[0,1,1]
	v_pk_fma_f32 v[68:69], s[18:19], v[0:1], v[4:5] op_sel_hi:[0,1,1]
	s_add_u32 s18, s16, s36
	s_addc_u32 s19, s17, 0
	ds_write_b128 v97, v[68:71] offset:8192
	v_lshlrev_b32_e32 v102, 16, v228
	v_and_b32_e32 v103, 0xffff0000, v228
	v_lshlrev_b32_e32 v104, 16, v229
	v_and_b32_e32 v105, 0xffff0000, v229
	v_mov_b32_e32 v106, v230
	v_lshlrev_b32_e32 v107, 16, v231
	v_lshlrev_b32_e32 v108, 16, v232
	s_nop 0
	v_readlane_b32 s16, v106, 0
	v_readlane_b32 s18, v107, 0
	v_readlane_b32 s20, v108, 0
	s_nop 1
	v_pk_mul_f32 v[4:5], s[20:21], v[102:103] op_sel_hi:[0,1]
	v_pk_mul_f32 v[12:13], s[20:21], v[104:105] op_sel_hi:[0,1]
	v_readlane_b32 s20, v108, 1
	v_pk_fma_f32 v[72:73], v[60:61], s[16:17], v[12:13] op_sel_hi:[1,0,1]
	v_pk_fma_f32 v[74:75], v[62:63], s[16:17], v[4:5] op_sel_hi:[1,0,1]
	v_readlane_b32 s16, v106, 1
	v_pk_mul_f32 v[20:21], s[20:21], v[104:105] op_sel_hi:[0,1]
	v_pk_mul_f32 v[30:31], s[20:21], v[102:103] op_sel_hi:[0,1]
	v_readlane_b32 s20, v108, 2
	v_pk_fma_f32 v[4:5], s[18:19], v[74:75], 0 op_sel_hi:[0,1,0]
	v_pk_fma_f32 v[12:13], s[18:19], v[72:73], 0 op_sel_hi:[0,1,0]
	v_readlane_b32 s18, v107, 1
	v_pk_fma_f32 v[68:69], v[64:65], s[16:17], v[30:31] op_sel_hi:[1,0,1]
	v_pk_fma_f32 v[70:71], v[66:67], s[16:17], v[20:21] op_sel_hi:[1,0,1]
	v_readlane_b32 s16, v106, 2
	v_pk_mul_f32 v[20:21], s[20:21], v[102:103] op_sel_hi:[0,1]
	v_pk_mul_f32 v[30:31], s[20:21], v[104:105] op_sel_hi:[0,1]
	v_readlane_b32 s20, v108, 3
	v_pk_fma_f32 v[12:13], s[18:19], v[70:71], v[12:13] op_sel_hi:[0,1,1]
	v_pk_fma_f32 v[4:5], s[18:19], v[68:69], v[4:5] op_sel_hi:[0,1,1]
	v_readlane_b32 s18, v107, 2
	v_pk_fma_f32 v[64:65], v[76:77], s[16:17], v[30:31] op_sel_hi:[1,0,1]
	v_pk_fma_f32 v[66:67], v[78:79], s[16:17], v[20:21] op_sel_hi:[1,0,1]
	v_readlane_b32 s16, v106, 3
	v_pk_mul_f32 v[20:21], s[20:21], v[104:105] op_sel_hi:[0,1]
	v_pk_mul_f32 v[30:31], s[20:21], v[102:103] op_sel_hi:[0,1]
	v_readlane_b32 s20, v108, 4
	v_pk_fma_f32 v[4:5], s[18:19], v[66:67], v[4:5] op_sel_hi:[0,1,1]
	v_pk_fma_f32 v[12:13], s[18:19], v[64:65], v[12:13] op_sel_hi:[0,1,1]
	v_readlane_b32 s18, v107, 3
	v_pk_fma_f32 v[60:61], v[80:81], s[16:17], v[30:31] op_sel_hi:[1,0,1]
; DI void gla_scan(const Params& P, LAS unsigned char* lds) {
;     ...
; #pragma unroll
;             for (int i = 0; i < 16; ++i) { const float a = __builtin_bit_cast(float, __builtin_amdgcn_readlane(__builtin_bit_cast(int, a_l), i));
;                 const float q = __builtin_bit_cast(float, __builtin_amdgcn_readlane(__builtin_bit_cast(int, q_l), i)), k = __builtin_bit_cast(float, __builtin_amdgcn_readlane(__builtin_bit_cast(int, k_l), i));
;                 S[i] = S[i] * a + v * k; po += S[i] * q; }
	v_pk_fma_f32 v[62:63], v[82:83], s[16:17], v[20:21] op_sel_hi:[1,0,1]
	v_readlane_b32 s16, v106, 4
	v_pk_mul_f32 v[20:21], s[20:21], v[102:103] op_sel_hi:[0,1]
	v_pk_mul_f32 v[30:31], s[20:21], v[104:105] op_sel_hi:[0,1]
	v_readlane_b32 s20, v108, 5
	v_pk_fma_f32 v[12:13], s[18:19], v[62:63], v[12:13] op_sel_hi:[0,1,1]
	v_pk_fma_f32 v[4:5], s[18:19], v[60:61], v[4:5] op_sel_hi:[0,1,1]
	v_readlane_b32 s18, v107, 4
	v_pk_fma_f32 v[46:47], v[48:49], s[16:17], v[30:31] op_sel_hi:[1,0,1]
	v_pk_fma_f32 v[48:49], v[84:85], s[16:17], v[20:21] op_sel_hi:[1,0,1]
	v_readlane_b32 s16, v106, 5
	v_pk_mul_f32 v[20:21], s[20:21], v[104:105] op_sel_hi:[0,1]
	v_pk_mul_f32 v[30:31], s[20:21], v[102:103] op_sel_hi:[0,1]
	v_readlane_b32 s20, v108, 6
	v_pk_fma_f32 v[4:5], s[18:19], v[48:49], v[4:5] op_sel_hi:[0,1,1]
	v_pk_fma_f32 v[12:13], s[18:19], v[46:47], v[12:13] op_sel_hi:[0,1,1]
	v_readlane_b32 s18, v107, 5
	v_pk_fma_f32 v[42:43], v[42:43], s[16:17], v[30:31] op_sel_hi:[1,0,1]
	v_pk_fma_f32 v[44:45], v[44:45], s[16:17], v[20:21] op_sel_hi:[1,0,1]
	v_readlane_b32 s16, v106, 6
	v_pk_mul_f32 v[20:21], s[20:21], v[102:103] op_sel_hi:[0,1]
	v_pk_mul_f32 v[30:31], s[20:21], v[104:105] op_sel_hi:[0,1]
	v_readlane_b32 s20, v108, 7
	v_pk_fma_f32 v[12:13], s[18:19], v[44:45], v[12:13] op_sel_hi:[0,1,1]
	v_pk_fma_f32 v[4:5], s[18:19], v[42:43], v[4:5] op_sel_hi:[0,1,1]
	v_readlane_b32 s18, v107, 6
	v_pk_fma_f32 v[38:39], v[40:41], s[16:17], v[30:31] op_sel_hi:[1,0,1]
	v_pk_fma_f32 v[40:41], v[86:87], s[16:17], v[20:21] op_sel_hi:[1,0,1]
	v_readlane_b32 s16, v106, 7
	v_pk_mul_f32 v[20:21], s[20:21], v[104:105] op_sel_hi:[0,1]
	v_pk_mul_f32 v[30:31], s[20:21], v[102:103] op_sel_hi:[0,1]
	v_readlane_b32 s20, v108, 8
	v_pk_fma_f32 v[4:5], s[18:19], v[40:41], v[4:5] op_sel_hi:[0,1,1]
	v_pk_fma_f32 v[12:13], s[18:19], v[38:39], v[12:13] op_sel_hi:[0,1,1]
	v_readlane_b32 s18, v107, 7
	v_pk_fma_f32 v[34:35], v[34:35], s[16:17], v[30:31] op_sel_hi:[1,0,1]
	v_pk_fma_f32 v[36:37], v[36:37], s[16:17], v[20:21] op_sel_hi:[1,0,1]
	v_readlane_b32 s16, v106, 8
	v_pk_mul_f32 v[20:21], s[20:21], v[102:103] op_sel_hi:[0,1]
	v_pk_mul_f32 v[30:31], s[20:21], v[104:105] op_sel_hi:[0,1]
	v_readlane_b32 s20, v108, 9
	v_pk_fma_f32 v[12:13], s[18:19], v[36:37], v[12:13] op_sel_hi:[0,1,1]
	v_pk_fma_f32 v[4:5], s[18:19], v[34:35], v[4:5] op_sel_hi:[0,1,1]
	v_readlane_b32 s18, v107, 8
	v_pk_fma_f32 v[30:31], v[32:33], s[16:17], v[30:31] op_sel_hi:[1,0,1]
	v_pk_fma_f32 v[32:33], v[88:89], s[16:17], v[20:21] op_sel_hi:[1,0,1]
	v_readlane_b32 s16, v106, 9
	v_pk_mul_f32 v[20:21], s[20:21], v[104:105] op_sel_hi:[0,1]
	v_pk_mul_f32 v[76:77], s[20:21], v[102:103] op_sel_hi:[0,1]
	v_readlane_b32 s20, v108, 10
	v_pk_fma_f32 v[4:5], s[18:19], v[32:33], v[4:5] op_sel_hi:[0,1,1]
	v_pk_fma_f32 v[12:13], s[18:19], v[30:31], v[12:13] op_sel_hi:[0,1,1]
	v_readlane_b32 s18, v107, 9
	v_pk_fma_f32 v[26:27], v[26:27], s[16:17], v[76:77] op_sel_hi:[1,0,1]
	v_pk_fma_f32 v[28:29], v[28:29], s[16:17], v[20:21] op_sel_hi:[1,0,1]
	v_readlane_b32 s16, v106, 10
	v_pk_mul_f32 v[76:77], s[20:21], v[102:103] op_sel_hi:[0,1]
	v_pk_mul_f32 v[20:21], s[20:21], v[104:105] op_sel_hi:[0,1]
	v_readlane_b32 s20, v108, 11
	v_pk_fma_f32 v[12:13], s[18:19], v[28:29], v[12:13] op_sel_hi:[0,1,1]
	v_pk_fma_f32 v[4:5], s[18:19], v[26:27], v[4:5] op_sel_hi:[0,1,1]
	v_readlane_b32 s18, v107, 10
	v_pk_fma_f32 v[20:21], v[22:23], s[16:17], v[20:21] op_sel_hi:[1,0,1]
	v_pk_fma_f32 v[22:23], v[90:91], s[16:17], v[76:77] op_sel_hi:[1,0,1]
	v_readlane_b32 s16, v106, 11
	v_pk_mul_f32 v[76:77], s[20:21], v[104:105] op_sel_hi:[0,1]
	v_pk_fma_f32 v[4:5], s[18:19], v[22:23], v[4:5] op_sel_hi:[0,1,1]
	v_pk_fma_f32 v[12:13], s[18:19], v[20:21], v[12:13] op_sel_hi:[0,1,1]
	v_readlane_b32 s18, v107, 11
	v_pk_mul_f32 v[78:79], s[20:21], v[102:103] op_sel_hi:[0,1]
	v_pk_fma_f32 v[18:19], v[18:19], s[16:17], v[76:77] op_sel_hi:[1,0,1]
	v_readlane_b32 s20, v108, 12
	v_pk_fma_f32 v[16:17], v[16:17], s[16:17], v[78:79] op_sel_hi:[1,0,1]
	v_pk_fma_f32 v[76:77], s[18:19], v[18:19], v[12:13] op_sel_hi:[0,1,1]
	v_readlane_b32 s16, v106, 12
	v_pk_mul_f32 v[78:79], s[20:21], v[102:103] op_sel_hi:[0,1]
	v_pk_mul_f32 v[12:13], s[20:21], v[104:105] op_sel_hi:[0,1]
	v_readlane_b32 s20, v108, 13
	v_pk_fma_f32 v[4:5], s[18:19], v[16:17], v[4:5] op_sel_hi:[0,1,1]
	v_readlane_b32 s18, v107, 12
	v_pk_fma_f32 v[12:13], v[14:15], s[16:17], v[12:13] op_sel_hi:[1,0,1]
	v_pk_fma_f32 v[14:15], v[92:93], s[16:17], v[78:79] op_sel_hi:[1,0,1]
	v_readlane_b32 s16, v106, 13
	v_pk_mul_f32 v[80:81], s[20:21], v[102:103] op_sel_hi:[0,1]
	v_pk_fma_f32 v[4:5], s[18:19], v[14:15], v[4:5] op_sel_hi:[0,1,1]
	v_pk_fma_f32 v[76:77], s[18:19], v[12:13], v[76:77] op_sel_hi:[0,1,1]
	v_readlane_b32 s18, v107, 13
	v_pk_mul_f32 v[78:79], s[20:21], v[104:105] op_sel_hi:[0,1]
	v_pk_fma_f32 v[8:9], v[8:9], s[16:17], v[80:81] op_sel_hi:[1,0,1]
	v_readlane_b32 s20, v108, 14
	v_pk_fma_f32 v[10:11], v[10:11], s[16:17], v[78:79] op_sel_hi:[1,0,1]
	v_pk_fma_f32 v[78:79], s[18:19], v[8:9], v[4:5] op_sel_hi:[0,1,1]
	v_readlane_b32 s16, v106, 14
	v_pk_mul_f32 v[80:81], s[20:21], v[102:103] op_sel_hi:[0,1]
	v_pk_mul_f32 v[4:5], s[20:21], v[104:105] op_sel_hi:[0,1]
	v_pk_fma_f32 v[76:77], s[18:19], v[10:11], v[76:77] op_sel_hi:[0,1,1]
	v_readlane_b32 s18, v107, 14
	v_pk_fma_f32 v[4:5], v[6:7], s[16:17], v[4:5] op_sel_hi:[1,0,1]
	v_pk_fma_f32 v[6:7], v[94:95], s[16:17], v[80:81] op_sel_hi:[1,0,1]
	v_readlane_b32 s20, v108, 15
	v_pk_fma_f32 v[80:81], s[18:19], v[6:7], v[78:79] op_sel_hi:[0,1,1]
	v_readlane_b32 s16, v106, 15
	v_pk_mul_f32 v[78:79], s[20:21], v[104:105] op_sel_hi:[0,1]
; #define LAS __attribute__((address_space(3)))
; DI float bflo(unsigned w) { return __uint_as_float(w << 16); }
; DI float bfhi(unsigned w) { return __uint_as_float(w & 0xffff0000u); }
; DI float bf2f(bf16_t b) { return __uint_as_float(((unsigned)b) << 16); }
; DI void gla_scan(const Params& P, LAS unsigned char* lds) {
;     ...
;         for (int t = 0; t < 4; ++t) { const int row = TP + 4 * b + t; const bf16_t* qk = QK + (size_t)row * 3072;
;             const u32x2 vw = *(const u32x2*)(qk + 1024 + h * 256 + v4); const f32x4 v = {bflo(vw.x), bfhi(vw.x), bflo(vw.y), bfhi(vw.y)};
;             f32x4 po = {0.f, 0.f, 0.f, 0.f};
;             const int dl = h * 128 + 16 * wid + (lane & 15);
;             const float a_l = SA[(size_t)(4 * b + t) * 512 + dl]; const float q_l = bf2f(qk[dl]), k_l = bf2f(qk[512 + dl]);
; #pragma unroll
;             for (int i = 0; i < 16; ++i) { const float a = __builtin_bit_cast(float, __builtin_amdgcn_readlane(__builtin_bit_cast(int, a_l), i));
;                 const float q = __builtin_bit_cast(float, __builtin_amdgcn_readlane(__builtin_bit_cast(int, q_l), i)), k = __builtin_bit_cast(float, __builtin_amdgcn_readlane(__builtin_bit_cast(int, k_l), i));
;                 S[i] = S[i] * a + v * k; po += S[i] * q; }
;             *(LAS f32x4*)(red + (t * 8 + wid) * 256 + v4) = po; }
	v_pk_mul_f32 v[82:83], s[20:21], v[102:103] op_sel_hi:[0,1]
	v_pk_fma_f32 v[76:77], s[18:19], v[4:5], v[76:77] op_sel_hi:[0,1,1]
	v_readlane_b32 s18, v107, 15
	v_pk_fma_f32 v[0:1], v[0:1], s[16:17], v[82:83] op_sel_hi:[1,0,1]
	v_pk_fma_f32 v[2:3], v[2:3], s[16:17], v[78:79] op_sel_hi:[1,0,1]
	s_add_u32 s16, s14, s36
	v_pk_fma_f32 v[78:79], s[18:19], v[2:3], v[76:77] op_sel_hi:[0,1,1]
	v_pk_fma_f32 v[76:77], s[18:19], v[0:1], v[80:81] op_sel_hi:[0,1,1]
	s_addc_u32 s17, s15, 0
	ds_write_b128 v97, v[76:79] offset:16384
	s_nop 0
	v_mov_b32_e32 v56, v236
	v_lshlrev_b32_e32 v57, 16, v237
	v_lshlrev_b32_e32 v86, 16, v238
	v_lshlrev_b32_e32 v76, 16, v234
	v_and_b32_e32 v77, 0xffff0000, v234
	v_lshlrev_b32_e32 v78, 16, v235
	v_and_b32_e32 v79, 0xffff0000, v235
	v_readlane_b32 s14, v56, 0
	v_readlane_b32 s16, v57, 0
	v_readlane_b32 s18, v86, 0
	s_nop 1
	v_pk_mul_f32 v[58:59], s[18:19], v[76:77] op_sel_hi:[0,1]
	v_pk_mul_f32 v[80:81], s[18:19], v[78:79] op_sel_hi:[0,1]
	v_readlane_b32 s18, v86, 1
	v_pk_fma_f32 v[82:83], v[72:73], s[14:15], v[80:81] op_sel_hi:[1,0,1]
	v_pk_fma_f32 v[80:81], v[74:75], s[14:15], v[58:59] op_sel_hi:[1,0,1]
	v_readlane_b32 s14, v56, 1
	v_pk_mul_f32 v[74:75], s[18:19], v[76:77] op_sel_hi:[0,1]
	v_pk_mul_f32 v[84:85], s[18:19], v[78:79] op_sel_hi:[0,1]
	v_readlane_b32 s18, v86, 2
	v_pk_fma_f32 v[58:59], s[16:17], v[80:81], 0 op_sel_hi:[0,1,0]
	v_pk_fma_f32 v[72:73], s[16:17], v[82:83], 0 op_sel_hi:[0,1,0]
	v_readlane_b32 s16, v57, 1
	v_pk_fma_f32 v[70:71], v[70:71], s[14:15], v[84:85] op_sel_hi:[1,0,1]
	v_pk_fma_f32 v[68:69], v[68:69], s[14:15], v[74:75] op_sel_hi:[1,0,1]
	v_readlane_b32 s14, v56, 2
	v_pk_mul_f32 v[74:75], s[18:19], v[78:79] op_sel_hi:[0,1]
	v_pk_fma_f32 v[84:85], s[16:17], v[70:71], v[72:73] op_sel_hi:[0,1,1]
	v_pk_fma_f32 v[58:59], s[16:17], v[68:69], v[58:59] op_sel_hi:[0,1,1]
	v_readlane_b32 s16, v57, 2
	v_pk_mul_f32 v[72:73], s[18:19], v[76:77] op_sel_hi:[0,1]
	v_pk_fma_f32 v[74:75], v[64:65], s[14:15], v[74:75] op_sel_hi:[1,0,1]
	v_readlane_b32 s18, v86, 3
	v_pk_fma_f32 v[72:73], v[66:67], s[14:15], v[72:73] op_sel_hi:[1,0,1]
	v_pk_fma_f32 v[64:65], s[16:17], v[74:75], v[84:85] op_sel_hi:[0,1,1]
	v_readlane_b32 s14, v56, 3
	v_pk_mul_f32 v[84:85], s[18:19], v[78:79] op_sel_hi:[0,1]
	v_pk_fma_f32 v[58:59], s[16:17], v[72:73], v[58:59] op_sel_hi:[0,1,1]
	v_readlane_b32 s16, v57, 3
	v_pk_mul_f32 v[66:67], s[18:19], v[76:77] op_sel_hi:[0,1]
	v_pk_fma_f32 v[62:63], v[62:63], s[14:15], v[84:85] op_sel_hi:[1,0,1]
	v_readlane_b32 s18, v86, 4
	v_pk_fma_f32 v[60:61], v[60:61], s[14:15], v[66:67] op_sel_hi:[1,0,1]
	v_pk_fma_f32 v[84:85], s[16:17], v[62:63], v[64:65] op_sel_hi:[0,1,1]
	v_readlane_b32 s14, v56, 4
	v_pk_mul_f32 v[64:65], s[18:19], v[76:77] op_sel_hi:[0,1]
	v_pk_mul_f32 v[66:67], s[18:19], v[78:79] op_sel_hi:[0,1]
	v_pk_fma_f32 v[58:59], s[16:17], v[60:61], v[58:59] op_sel_hi:[0,1,1]
	v_readlane_b32 s16, v57, 4
	v_pk_fma_f32 v[66:67], v[46:47], s[14:15], v[66:67] op_sel_hi:[1,0,1]
	v_pk_fma_f32 v[64:65], v[48:49], s[14:15], v[64:65] op_sel_hi:[1,0,1]
	v_readlane_b32 s18, v86, 5
	v_pk_fma_f32 v[46:47], s[16:17], v[64:65], v[58:59] op_sel_hi:[0,1,1]
	v_pk_fma_f32 v[48:49], s[16:17], v[66:67], v[84:85] op_sel_hi:[0,1,1]
	v_readlane_b32 s14, v56, 5
	v_pk_mul_f32 v[58:59], s[18:19], v[76:77] op_sel_hi:[0,1]
	v_pk_mul_f32 v[84:85], s[18:19], v[78:79] op_sel_hi:[0,1]
	v_readlane_b32 s16, v57, 5
	v_pk_fma_f32 v[44:45], v[44:45], s[14:15], v[84:85] op_sel_hi:[1,0,1]
	v_pk_fma_f32 v[42:43], v[42:43], s[14:15], v[58:59] op_sel_hi:[1,0,1]
	v_readlane_b32 s18, v86, 6
	v_pk_fma_f32 v[58:59], s[16:17], v[44:45], v[48:49] op_sel_hi:[0,1,1]
	v_pk_fma_f32 v[84:85], s[16:17], v[42:43], v[46:47] op_sel_hi:[0,1,1]
	v_readlane_b32 s14, v56, 6
	v_pk_mul_f32 v[46:47], s[18:19], v[76:77] op_sel_hi:[0,1]
	v_pk_mul_f32 v[48:49], s[18:19], v[78:79] op_sel_hi:[0,1]
	v_readlane_b32 s16, v57, 6
	v_pk_fma_f32 v[48:49], v[38:39], s[14:15], v[48:49] op_sel_hi:[1,0,1]
	v_pk_fma_f32 v[46:47], v[40:41], s[14:15], v[46:47] op_sel_hi:[1,0,1]
	v_readlane_b32 s18, v86, 7
	v_pk_fma_f32 v[38:39], s[16:17], v[46:47], v[84:85] op_sel_hi:[0,1,1]
	v_pk_fma_f32 v[40:41], s[16:17], v[48:49], v[58:59] op_sel_hi:[0,1,1]
	v_readlane_b32 s14, v56, 7
	v_pk_mul_f32 v[58:59], s[18:19], v[76:77] op_sel_hi:[0,1]
	v_pk_mul_f32 v[84:85], s[18:19], v[78:79] op_sel_hi:[0,1]
	v_readlane_b32 s16, v57, 7
	v_pk_fma_f32 v[36:37], v[36:37], s[14:15], v[84:85] op_sel_hi:[1,0,1]
	v_pk_fma_f32 v[34:35], v[34:35], s[14:15], v[58:59] op_sel_hi:[1,0,1]
	v_readlane_b32 s18, v86, 8
	v_pk_fma_f32 v[58:59], s[16:17], v[36:37], v[40:41] op_sel_hi:[0,1,1]
	v_pk_fma_f32 v[84:85], s[16:17], v[34:35], v[38:39] op_sel_hi:[0,1,1]
	v_readlane_b32 s14, v56, 8
	v_pk_mul_f32 v[38:39], s[18:19], v[76:77] op_sel_hi:[0,1]
	v_pk_mul_f32 v[40:41], s[18:19], v[78:79] op_sel_hi:[0,1]
	v_readlane_b32 s16, v57, 8
	v_pk_fma_f32 v[40:41], v[30:31], s[14:15], v[40:41] op_sel_hi:[1,0,1]
	v_pk_fma_f32 v[38:39], v[32:33], s[14:15], v[38:39] op_sel_hi:[1,0,1]
	v_readlane_b32 s18, v86, 9
	v_pk_fma_f32 v[30:31], s[16:17], v[38:39], v[84:85] op_sel_hi:[0,1,1]
	v_pk_fma_f32 v[32:33], s[16:17], v[40:41], v[58:59] op_sel_hi:[0,1,1]
	v_readlane_b32 s14, v56, 9
	v_pk_mul_f32 v[58:59], s[18:19], v[76:77] op_sel_hi:[0,1]
	v_pk_mul_f32 v[84:85], s[18:19], v[78:79] op_sel_hi:[0,1]
	v_readlane_b32 s16, v57, 9
	v_pk_fma_f32 v[28:29], v[28:29], s[14:15], v[84:85] op_sel_hi:[1,0,1]
	v_pk_fma_f32 v[26:27], v[26:27], s[14:15], v[58:59] op_sel_hi:[1,0,1]
	v_readlane_b32 s18, v86, 10
	v_pk_fma_f32 v[58:59], s[16:17], v[28:29], v[32:33] op_sel_hi:[0,1,1]
	v_pk_fma_f32 v[84:85], s[16:17], v[26:27], v[30:31] op_sel_hi:[0,1,1]
; #define LAS __attribute__((address_space(3)))
; DI bf16_t f2bf(float f) { return (bf16_t)(pk2(f, 0.f) & 0xffffu); }
; #define LDS_BARRIER() do { asm volatile("s_waitcnt lgkmcnt(0)" ::: "memory"); __builtin_amdgcn_s_barrier(); asm volatile("" ::: "memory"); } while (0)
; DI void gla_scan(const Params& P, LAS unsigned char* lds) {
;     ...
;                 S[i] = S[i] * a + v * k; po += S[i] * q; }
;             *(LAS f32x4*)(red + (t * 8 + wid) * 256 + v4) = po; }
;         float* SO = P.out + OUT_GLAS + ((size_t)(b * 4 + h) * 128 + 16 * wid) * 256 + v4;
; #pragma unroll
;         for (int i = 0; i < 16; ++i) *(f32x4*)(SO + (size_t)i * 256) = S[i];
;         LDS_BARRIER();
; #pragma unroll
;         for (int i = 0; i < 2; ++i) { const int idx = tid + 512 * i, t = idx >> 8, v = idx & 255; float o = 0.f;
; #pragma unroll
;             for (int w = 0; w < 8; ++w) o += red[(t * 8 + w) * 256 + v];
;             const int row = TP + 4 * b + t; OB[(size_t)row * DM + h * 256 + v] = f2bf(o); }
;         LDS_BARRIER();
	v_readlane_b32 s14, v56, 10
	v_pk_mul_f32 v[30:31], s[18:19], v[76:77] op_sel_hi:[0,1]
	v_pk_mul_f32 v[32:33], s[18:19], v[78:79] op_sel_hi:[0,1]
	v_readlane_b32 s16, v57, 10
	v_pk_fma_f32 v[32:33], v[20:21], s[14:15], v[32:33] op_sel_hi:[1,0,1]
	v_pk_fma_f32 v[30:31], v[22:23], s[14:15], v[30:31] op_sel_hi:[1,0,1]
	v_readlane_b32 s18, v86, 11
	v_pk_fma_f32 v[20:21], s[16:17], v[30:31], v[84:85] op_sel_hi:[0,1,1]
	v_pk_fma_f32 v[22:23], s[16:17], v[32:33], v[58:59] op_sel_hi:[0,1,1]
	v_readlane_b32 s14, v56, 11
	v_pk_mul_f32 v[58:59], s[18:19], v[76:77] op_sel_hi:[0,1]
	v_pk_mul_f32 v[84:85], s[18:19], v[78:79] op_sel_hi:[0,1]
	v_readlane_b32 s16, v57, 11
	v_pk_fma_f32 v[18:19], v[18:19], s[14:15], v[84:85] op_sel_hi:[1,0,1]
	v_pk_fma_f32 v[16:17], v[16:17], s[14:15], v[58:59] op_sel_hi:[1,0,1]
	v_readlane_b32 s18, v86, 12
	v_pk_fma_f32 v[58:59], s[16:17], v[18:19], v[22:23] op_sel_hi:[0,1,1]
	v_pk_fma_f32 v[84:85], s[16:17], v[16:17], v[20:21] op_sel_hi:[0,1,1]
	v_readlane_b32 s14, v56, 12
	v_pk_mul_f32 v[20:21], s[18:19], v[76:77] op_sel_hi:[0,1]
	v_pk_mul_f32 v[22:23], s[18:19], v[78:79] op_sel_hi:[0,1]
	v_readlane_b32 s16, v57, 12
	v_pk_fma_f32 v[22:23], v[12:13], s[14:15], v[22:23] op_sel_hi:[1,0,1]
	v_pk_fma_f32 v[20:21], v[14:15], s[14:15], v[20:21] op_sel_hi:[1,0,1]
	v_readlane_b32 s18, v86, 13
	v_pk_fma_f32 v[12:13], s[16:17], v[20:21], v[84:85] op_sel_hi:[0,1,1]
	v_pk_fma_f32 v[14:15], s[16:17], v[22:23], v[58:59] op_sel_hi:[0,1,1]
	v_readlane_b32 s14, v56, 13
	v_pk_mul_f32 v[58:59], s[18:19], v[76:77] op_sel_hi:[0,1]
	v_pk_mul_f32 v[84:85], s[18:19], v[78:79] op_sel_hi:[0,1]
	v_readlane_b32 s16, v57, 13
	v_pk_fma_f32 v[10:11], v[10:11], s[14:15], v[84:85] op_sel_hi:[1,0,1]
	v_pk_fma_f32 v[8:9], v[8:9], s[14:15], v[58:59] op_sel_hi:[1,0,1]
	v_readlane_b32 s18, v86, 14
	v_pk_fma_f32 v[58:59], s[16:17], v[10:11], v[14:15] op_sel_hi:[0,1,1]
	v_pk_fma_f32 v[84:85], s[16:17], v[8:9], v[12:13] op_sel_hi:[0,1,1]
	v_readlane_b32 s14, v56, 14
	v_pk_mul_f32 v[12:13], s[18:19], v[76:77] op_sel_hi:[0,1]
	v_pk_mul_f32 v[14:15], s[18:19], v[78:79] op_sel_hi:[0,1]
	v_readlane_b32 s16, v57, 14
	v_pk_fma_f32 v[14:15], v[4:5], s[14:15], v[14:15] op_sel_hi:[1,0,1]
	v_pk_fma_f32 v[12:13], v[6:7], s[14:15], v[12:13] op_sel_hi:[1,0,1]
	v_readlane_b32 s18, v86, 15
	v_pk_fma_f32 v[4:5], s[16:17], v[12:13], v[84:85] op_sel_hi:[0,1,1]
	v_pk_fma_f32 v[6:7], s[16:17], v[14:15], v[58:59] op_sel_hi:[0,1,1]
	v_readlane_b32 s14, v56, 15
	v_readlane_b32 s16, v57, 15
	v_pk_mul_f32 v[56:57], s[18:19], v[76:77] op_sel_hi:[0,1]
	v_pk_mul_f32 v[58:59], s[18:19], v[78:79] op_sel_hi:[0,1]
	v_pk_fma_f32 v[2:3], v[2:3], s[14:15], v[58:59] op_sel_hi:[1,0,1]
	v_pk_fma_f32 v[0:1], v[0:1], s[14:15], v[56:57] op_sel_hi:[1,0,1]
	v_pk_fma_f32 v[6:7], s[16:17], v[2:3], v[6:7] op_sel_hi:[0,1,1]
	v_pk_fma_f32 v[4:5], s[16:17], v[0:1], v[4:5] op_sel_hi:[0,1,1]
	ds_write_b128 v97, v[4:7] offset:24576
	v_lshl_add_u64 v[4:5], v[54:55], 0, s[12:13]
	v_add_co_u32_e32 v6, vcc, s86, v4
	global_store_dwordx4 v[4:5], v[80:83], off
	global_store_dwordx4 v[4:5], v[68:71], off offset:1024
	global_store_dwordx4 v[4:5], v[72:75], off offset:2048
	global_store_dwordx4 v[4:5], v[60:63], off offset:3072
	v_addc_co_u32_e32 v7, vcc, 0, v5, vcc
	v_add_co_u32_e32 v56, vcc, s92, v4
	s_nop 1
	v_addc_co_u32_e32 v57, vcc, 0, v5, vcc
	v_add_co_u32_e32 v4, vcc, s91, v4
	global_store_dwordx4 v[56:57], v[64:67], off offset:-4096
	global_store_dwordx4 v[6:7], v[42:45], off offset:1024
	global_store_dwordx4 v[6:7], v[46:49], off offset:2048
	global_store_dwordx4 v[6:7], v[34:37], off offset:3072
	global_store_dwordx4 v[56:57], v[38:41], off
	global_store_dwordx4 v[56:57], v[26:29], off offset:1024
	global_store_dwordx4 v[56:57], v[30:33], off offset:2048
	global_store_dwordx4 v[56:57], v[16:19], off offset:3072
	v_addc_co_u32_e32 v5, vcc, 0, v5, vcc
	global_store_dwordx4 v[4:5], v[20:23], off
	global_store_dwordx4 v[4:5], v[8:11], off offset:1024
	global_store_dwordx4 v[4:5], v[12:15], off offset:2048
	global_store_dwordx4 v[4:5], v[0:3], off offset:3072
	s_waitcnt lgkmcnt(0)
	s_barrier
	ds_read2st64_b32 v[2:3], v100 offset1:4
	v_lshl_add_u64 v[0:1], v[50:51], 0, s[36:37]
	s_waitcnt lgkmcnt(0)
	v_add_f32_e32 v2, 0, v2
	v_add_f32_e32 v4, v2, v3
	ds_read2st64_b32 v[2:3], v100 offset0:8 offset1:12
	s_waitcnt lgkmcnt(0)
	v_add_f32_e32 v2, v4, v2
	v_add_f32_e32 v4, v2, v3
	ds_read2st64_b32 v[2:3], v100 offset0:16 offset1:20
	s_waitcnt lgkmcnt(0)
	v_add_f32_e32 v2, v4, v2
	v_add_f32_e32 v4, v2, v3
	ds_read2st64_b32 v[2:3], v100 offset0:24 offset1:28
	s_waitcnt lgkmcnt(0)
	v_add_f32_e32 v2, v4, v2
	v_add_f32_e32 v3, v2, v3
	v_or_b32_e32 v2, s3, v24
	v_cvt_pk_bf16_f32 v4, v3, s0
	v_ashrrev_i32_e32 v3, 31, v2
	v_lshlrev_b64 v[2:3], 11, v[2:3]
	v_lshl_add_u64 v[2:3], v[0:1], 0, v[2:3]
	global_store_short v[2:3], v4, off
	ds_read2st64_b32 v[2:3], v101 offset1:4
	s_waitcnt lgkmcnt(0)
	v_add_f32_e32 v2, 0, v2
	v_add_f32_e32 v4, v2, v3
	ds_read2st64_b32 v[2:3], v101 offset0:8 offset1:12
	s_waitcnt lgkmcnt(0)
	v_add_f32_e32 v2, v4, v2
	v_add_f32_e32 v4, v2, v3
	ds_read2st64_b32 v[2:3], v101 offset0:16 offset1:20
	s_waitcnt lgkmcnt(0)
	v_add_f32_e32 v2, v4, v2
	v_add_f32_e32 v4, v2, v3
	ds_read2st64_b32 v[2:3], v101 offset0:24 offset1:28
	s_waitcnt lgkmcnt(0)
	v_add_f32_e32 v2, v4, v2
	v_add_f32_e32 v3, v2, v3
	v_or_b32_e32 v2, s3, v98
	v_cvt_pk_bf16_f32 v4, v3, s0
	v_ashrrev_i32_e32 v3, 31, v2
	v_lshlrev_b64 v[2:3], 11, v[2:3]
	v_lshl_add_u64 v[0:1], v[0:1], 0, v[2:3]
	global_store_short v[0:1], v4, off
	s_waitcnt lgkmcnt(0)
	s_barrier
	s_load_dword s3, s[50:51], 0x0
	s_waitcnt lgkmcnt(0)
	s_add_i32 s6, s3, s6
	s_cmpk_gt_i32 s6, 0x1ff
	s_cbranch_scc0 .LBB0_1096
